# block-id permutation variant: 6-bit bit reversal of the in-XCD index
# baseline (speedup 1.0000x reference)
.Lrole_done:
	s_lshl_b32 s98, s98, 1
	s_or_b32 s99, s99, s98
	s_lshl_b32 s100, s100, 2
	s_or_b32 s101, s99, s100
	v_readlane_b32 s98, v252, 0
	s_lshr_b32 s98, s98, 3
	s_and_b32 s98, s98, 0xff
	s_lshl_b32 s98, s98, 8
	s_or_b32 s101, s101, s98
	v_readlane_b32 s98, v252, 0
	s_lshr_b32 s99, s98, 3
	s_and_b32 s98, s98, 7
	s_brev_b32 s99, s99
	s_lshr_b32 s99, s99, 26
	s_lshl_b32 s99, s99, 3
	s_or_b32 s98, s98, s99
	s_nop 0
	v_writelane_b32 v252, s98, 0
	s_load_dwordx2 s[52:53], s[0:1], 0x210
	s_waitcnt lgkmcnt(0)
	s_cmp_ge_i32 s52, s53
	s_cbranch_scc1 .Lend_near
	s_load_dwordx2 s[22:23], s[0:1], 0x1a8
	s_load_dwordx16 s[56:71], s[0:1], 0x0
	s_load_dwordx16 s[36:51], s[0:1], 0x40
	s_load_dwordx16 s[4:19], s[0:1], 0x80
	v_lshrrev_b32_e32 v1, 20, v0
	v_lshrrev_b32_e32 v0, 10, v0
	v_or_b32_e32 v0, v0, v1
	s_mov_b32 s97, 0
	s_waitcnt lgkmcnt(0)
	v_writelane_b32 v252, s4, 5
	s_movk_i32 s55, 0x4000
	v_mov_b32_e32 v2, 0
	v_writelane_b32 v252, s5, 6
	v_writelane_b32 v252, s6, 7
	v_writelane_b32 v252, s7, 8
	v_writelane_b32 v252, s8, 9
	v_writelane_b32 v252, s9, 10
	v_writelane_b32 v252, s10, 11
	v_writelane_b32 v252, s11, 12
	v_writelane_b32 v252, s12, 13
	v_writelane_b32 v252, s13, 14
	v_writelane_b32 v252, s14, 15
	v_writelane_b32 v252, s15, 16
	v_writelane_b32 v252, s16, 17
	v_writelane_b32 v252, s17, 18
	v_writelane_b32 v252, s18, 19
	v_writelane_b32 v252, s19, 20
	s_load_dwordx16 s[4:19], s[0:1], 0xc0
	s_mov_b32 s28, 0x10000
	v_mov_b32_e32 v198, 0x358637bd
	s_movk_i32 s96, 0x43ff
	s_mov_b32 s29, 0x20000
	s_waitcnt lgkmcnt(0)
	v_writelane_b32 v252, s4, 21
	v_mov_b32_e32 v199, 0x10000
	s_movk_i32 s33, 0x110
	v_writelane_b32 v252, s5, 22
	v_writelane_b32 v252, s6, 23
	v_writelane_b32 v252, s7, 24
	v_writelane_b32 v252, s8, 25
	v_writelane_b32 v252, s9, 26
	v_writelane_b32 v252, s10, 27
	v_writelane_b32 v252, s11, 28
	v_writelane_b32 v252, s12, 29
	v_writelane_b32 v252, s13, 30
	v_writelane_b32 v252, s14, 31
	v_writelane_b32 v252, s15, 32
	v_writelane_b32 v252, s16, 33
	v_writelane_b32 v252, s17, 34
	v_writelane_b32 v252, s18, 35
	v_writelane_b32 v252, s19, 36
	s_load_dwordx16 s[4:19], s[0:1], 0x100
	v_mov_b32_e32 v201, 0x3ecc95a3
	v_mov_b64_e32 v[212:213], 0xe00
	v_mov_b64_e32 v[196:197], 0x3600
	v_mov_b32_e32 v204, 0x7f800000
	s_waitcnt lgkmcnt(0)
	v_writelane_b32 v252, s4, 37
	v_mov_b32_e32 v206, 0x41b17218
	v_mov_b32_e32 v136, 0x3f317218
	v_writelane_b32 v252, s5, 38
	v_writelane_b32 v252, s6, 39
	v_writelane_b32 v252, s7, 40
	v_writelane_b32 v252, s8, 41
	v_writelane_b32 v252, s9, 42
	v_writelane_b32 v252, s10, 43
	v_writelane_b32 v252, s11, 44
	v_writelane_b32 v252, s12, 45
	v_writelane_b32 v252, s13, 46
	v_writelane_b32 v252, s14, 47
	v_writelane_b32 v252, s15, 48
	v_writelane_b32 v252, s16, 49
	v_writelane_b32 v252, s17, 50
	v_writelane_b32 v252, s18, 51
	v_writelane_b32 v252, s19, 52
	s_load_dwordx16 s[72:87], s[0:1], 0x140
	s_load_dwordx16 s[4:19], s[0:1], 0x1b0
	v_mov_b32_e32 v203, 0x7fc00000
	v_mov_b32_e32 v195, 0xff800000
	v_mov_b32_e32 v205, 0xe400
	v_mov_b32_e32 v200, 0x9f00
	s_waitcnt lgkmcnt(0)
	v_writelane_b32 v252, s4, 53
	v_mov_b32_e32 v207, 0x42800000
	s_nop 0
	v_writelane_b32 v252, s5, 54
	v_writelane_b32 v252, s6, 55
	v_writelane_b32 v252, s7, 56
	v_writelane_b32 v253, s15, 0
	v_writelane_b32 v252, s8, 57
	v_writelane_b32 v253, s16, 1
	v_writelane_b32 v252, s9, 58
	v_writelane_b32 v253, s17, 2
	v_writelane_b32 v252, s10, 59
	v_writelane_b32 v253, s18, 3
	v_writelane_b32 v252, s11, 60
	v_writelane_b32 v253, s19, 4
	s_load_dwordx8 s[4:11], s[0:1], 0x1f0
	s_add_u32 s0, s0, 0x218
	s_addc_u32 s1, s1, 0
	v_writelane_b32 v252, s12, 61
	v_writelane_b32 v252, s13, 62
	s_waitcnt lgkmcnt(0)
	v_writelane_b32 v253, s4, 5
	v_writelane_b32 v252, s14, 63
	s_nop 0
	v_writelane_b32 v253, s5, 6
	v_writelane_b32 v253, s6, 7
	v_writelane_b32 v253, s7, 8
	v_writelane_b32 v253, s8, 9
	v_writelane_b32 v253, s9, 10
	v_writelane_b32 v253, s10, 11
	v_writelane_b32 v253, s11, 12
	v_writelane_b32 v253, s0, 13
	s_nop 1
	v_writelane_b32 v253, s1, 14
	s_add_u32 s0, s88, 0x200
	s_addc_u32 s1, s89, 0
	v_writelane_b32 v253, s0, 15
	s_nop 1
	v_writelane_b32 v253, s1, 16
	s_add_u32 s0, s88, 0x1000
	s_addc_u32 s1, s89, 0
	v_writelane_b32 v253, s0, 17
	s_nop 1
	v_writelane_b32 v253, s1, 18
	s_add_u32 s0, s88, 0x1100
	s_addc_u32 s1, s89, 0
	v_writelane_b32 v253, s0, 19
	s_nop 1
	v_writelane_b32 v253, s1, 20
	s_add_u32 s0, s88, 0x1200
	s_addc_u32 s1, s89, 0
	v_writelane_b32 v253, s0, 21
	s_nop 1
	v_writelane_b32 v253, s1, 22
	s_add_u32 s0, s88, 0x1300
	s_addc_u32 s1, s89, 0
	v_writelane_b32 v253, s0, 23
	s_cmp_eq_u32 s20, 15
	s_nop 0
	v_writelane_b32 v253, s1, 24
	s_cselect_b64 s[0:1], -1, 0
	v_writelane_b32 v253, s0, 25
	s_cmp_eq_u32 s20, 14
	s_nop 0
	v_writelane_b32 v253, s1, 26
	s_cselect_b64 s[0:1], -1, 0
	v_writelane_b32 v253, s0, 27
	s_cmp_eq_u32 s20, 13
	s_nop 0
	v_writelane_b32 v253, s1, 28
	s_cselect_b64 s[0:1], -1, 0
	v_writelane_b32 v253, s0, 29
	s_cmp_eq_u32 s20, 12
	s_nop 0
	v_writelane_b32 v253, s1, 30
	s_cselect_b64 s[0:1], -1, 0
	v_writelane_b32 v253, s0, 31
	s_cmp_eq_u32 s20, 11
	s_nop 0
	v_writelane_b32 v253, s1, 32
	s_cselect_b64 s[0:1], -1, 0
	v_writelane_b32 v253, s0, 33
	s_cmp_eq_u32 s20, 10
	s_nop 0
	v_writelane_b32 v253, s1, 34
	s_cselect_b64 s[0:1], -1, 0
	v_writelane_b32 v253, s0, 35
	s_cmp_eq_u32 s20, 9
	s_nop 0
	v_writelane_b32 v253, s1, 36
	s_cselect_b64 s[0:1], -1, 0
	v_writelane_b32 v253, s0, 37
	s_cmp_eq_u32 s20, 8
	s_nop 0
	v_writelane_b32 v253, s1, 38
	s_cselect_b64 s[0:1], -1, 0
	v_writelane_b32 v253, s0, 39
	s_cmp_eq_u32 s20, 7
	s_nop 0
	v_writelane_b32 v253, s1, 40
	s_cselect_b64 s[0:1], -1, 0
	v_writelane_b32 v253, s0, 41
	s_cmp_eq_u32 s20, 6
	s_nop 0
	v_writelane_b32 v253, s1, 42
	s_cselect_b64 s[0:1], -1, 0
	v_writelane_b32 v253, s0, 43
	s_cmp_eq_u32 s20, 5
	s_nop 0
	v_writelane_b32 v253, s1, 44
	s_cselect_b64 s[0:1], -1, 0
	v_writelane_b32 v253, s0, 45
	s_cmp_eq_u32 s20, 4
	s_nop 0
	v_writelane_b32 v253, s1, 46
	s_cselect_b64 s[0:1], -1, 0
	v_writelane_b32 v253, s0, 47
	s_cmp_eq_u32 s20, 3
	s_nop 0
	v_writelane_b32 v253, s1, 48
	s_cselect_b64 s[0:1], -1, 0
	v_writelane_b32 v253, s0, 49
	s_cmp_eq_u32 s20, 2
	s_nop 0
	v_writelane_b32 v253, s1, 50
	s_cselect_b64 s[0:1], -1, 0
	v_writelane_b32 v253, s0, 51
	s_cmp_eq_u32 s20, 1
	s_nop 0
	v_writelane_b32 v253, s1, 52
	s_cselect_b64 s[0:1], -1, 0
	v_writelane_b32 v253, s0, 53
	s_cmp_eq_u32 s20, 0
	s_nop 0
	v_writelane_b32 v253, s1, 54
	s_cselect_b64 s[0:1], -1, 0
	v_writelane_b32 v253, s0, 55
	s_nop 1
	v_writelane_b32 v253, s1, 56
	s_lshl_b32 s0, s20, 8
	s_add_u32 s0, s88, s0
	s_addc_u32 s1, s89, 0
	s_add_u32 s2, s0, 0x1400
	s_addc_u32 s3, s1, 0
	v_writelane_b32 v253, s2, 57
	s_add_u32 s0, s0, 0x2400
	s_addc_u32 s1, s1, 0
	v_writelane_b32 v253, s3, 58
	v_writelane_b32 v253, s0, 59
	v_readlane_b32 s3, v252, 0
	s_nop 0
	v_writelane_b32 v253, s1, 60
	s_add_u32 s0, s88, 0x3400
	s_addc_u32 s1, s89, 0
	v_writelane_b32 v253, s0, 61
	s_nop 1
	v_writelane_b32 v253, s1, 62
	s_add_u32 s0, s88, 0x3500
	s_addc_u32 s1, s89, 0
	v_writelane_b32 v253, s0, 63
	s_cmp_lt_i32 s53, 0
	s_nop 0
	v_writelane_b32 v254, s1, 0
	s_cselect_b64 s[0:1], -1, 0
	v_writelane_b32 v254, s0, 1
	s_nop 1
	v_writelane_b32 v254, s1, 2
	s_movk_i32 s0, 0x3ff
	v_and_or_b32 v0, v0, s0, v194
	v_cmp_eq_u32_e64 s[0:1], 0, v0
	s_nop 1
	v_writelane_b32 v254, s0, 3
	s_nop 1
	v_writelane_b32 v254, s1, 4
	s_lshl_b32 s0, s3, 2
	v_writelane_b32 v254, s0, 5
	s_add_u32 s0, s42, 0x1000
	v_writelane_b32 v254, s36, 6
	s_addc_u32 s1, s43, 0
	s_cmp_lg_u64 s[84:85], 0
	v_writelane_b32 v254, s37, 7
	v_writelane_b32 v254, s38, 8
	v_writelane_b32 v254, s39, 9
	v_writelane_b32 v254, s40, 10
	v_writelane_b32 v254, s41, 11
	v_writelane_b32 v254, s42, 12
	v_writelane_b32 v254, s43, 13
	v_writelane_b32 v254, s44, 14
	v_writelane_b32 v254, s45, 15
	v_writelane_b32 v254, s46, 16
	v_writelane_b32 v254, s47, 17
	v_writelane_b32 v254, s48, 18
	v_writelane_b32 v254, s49, 19
	v_writelane_b32 v254, s50, 20
	v_writelane_b32 v254, s51, 21
	v_writelane_b32 v254, s0, 22
	s_mov_b64 s[36:37], 0x800
	s_nop 0
	v_writelane_b32 v254, s1, 23
	s_cselect_b64 s[0:1], -1, 0
	v_writelane_b32 v254, s0, 24
	s_cmpk_lt_i32 s3, 0x1560
	s_nop 0
	v_writelane_b32 v254, s1, 25
	s_cselect_b64 s[0:1], -1, 0
	v_writelane_b32 v254, s0, 26
	s_cmp_lg_u64 s[76:77], 0
	s_nop 0
	v_writelane_b32 v254, s1, 27
	s_cselect_b64 s[0:1], -1, 0
	v_writelane_b32 v254, s0, 28
	s_and_b32 s4, s3, 7
	s_lshl_b32 s2, s3, 4
	v_writelane_b32 v254, s1, 29
	s_lshr_b32 s0, s3, 3
	s_lshl_b32 s1, s4, 6
	v_writelane_b32 v254, s0, 30
	s_add_i32 s0, s1, s0
	v_writelane_b32 v254, s1, 31
	s_lshl_b32 s0, s0, 4
	s_and_b32 s2, s2, 0x380
	s_and_b32 s1, s0, 0xfffffc00
	v_writelane_b32 v254, s2, 32
	s_and_b32 s0, s0, 0x380
	v_writelane_b32 v254, s0, 33
	s_lshl_b32 s0, s3, 1
	s_and_b32 s0, s0, 0x7fffff80
	s_or_b32 s1, s1, s2
	s_addk_i32 s0, 0x4000
	v_writelane_b32 v254, s0, 34
	s_add_i32 s54, s1, 0x2000
	s_lshl_b32 s0, s4, 22
	v_writelane_b32 v254, s1, 35
	s_add_u32 s0, s80, s0
	v_writelane_b32 v254, s4, 36
	s_addc_u32 s1, s81, 0
	v_writelane_b32 v254, s0, 37
	s_nop 1
	v_writelane_b32 v254, s1, 38
	s_add_i32 s1, s22, -1
	s_mul_i32 s0, s1, 0x60
	v_writelane_b32 v254, s0, 39
	s_mul_i32 s0, s1, 0xa0
	v_writelane_b32 v254, s0, 40
	s_ashr_i32 s0, s1, 31
	v_writelane_b32 v254, s0, 41
	v_writelane_b32 v254, s22, 42
	s_sub_i32 s0, 1, s22
	s_max_i32 s0, s1, s0
	v_cvt_f32_u32_e32 v0, s0
	v_writelane_b32 v254, s23, 43
	v_writelane_b32 v254, s1, 44
	v_writelane_b32 v254, s0, 45
	v_rcp_iflag_f32_e32 v0, v0
	s_sub_i32 s0, 0, s0
	v_mul_f32_e32 v0, 0x4f7ffffe, v0
	v_cvt_u32_f32_e32 v0, v0
	s_nop 0
	v_readfirstlane_b32 s1, v0
	s_mul_i32 s0, s0, s1
	s_mul_hi_u32 s0, s1, s0
	s_add_i32 s0, s1, s0
	v_writelane_b32 v254, s0, 46
	s_add_u32 s0, s78, 64
	s_addc_u32 s1, s79, 0
	v_writelane_b32 v254, s0, 47
	v_mbcnt_lo_u32_b32 v0, -1, 0
	s_nop 0
	v_writelane_b32 v254, s1, 48
	v_readlane_b32 s0, v252, 1
	v_readlane_b32 s1, v252, 2
	s_add_u32 s2, s0, 0x100
	s_addc_u32 s3, s1, 0
	v_writelane_b32 v254, s2, 49
	v_mbcnt_hi_u32_b32 v202, -1, v0
	s_nop 0
	v_writelane_b32 v254, s3, 50
	s_add_u32 s2, s0, 0x140
	s_addc_u32 s3, s1, 0
	v_writelane_b32 v254, s2, 51
	s_nop 1
	v_writelane_b32 v254, s3, 52
	s_add_u32 s2, s0, 0x180
	s_addc_u32 s3, s1, 0
	v_writelane_b32 v254, s2, 53
	s_add_u32 s0, s0, 0x1c0
	s_addc_u32 s1, s1, 0
	v_writelane_b32 v254, s3, 54
	v_writelane_b32 v254, s0, 55
	s_mov_b32 s2, s52
	s_nop 0
	v_writelane_b32 v254, s1, 56
	s_add_u32 s0, s78, 0x2c00
	s_addc_u32 s1, s79, 0
	v_writelane_b32 v254, s0, 57
	s_nop 1
	v_writelane_b32 v254, s1, 58
	v_writelane_b32 v254, s54, 59
	v_writelane_b32 v254, s52, 60
	s_nop 1
	v_writelane_b32 v254, s53, 61
	s_branch .LBB0_9
